# sample-row routine: norm weight/shift/scale rows fetched into LDS by LDS-DMA together with the slab loads, read back with ds_read after the sum
# baseline (speedup 1.0000x reference)
.Lsn_ready:
	v_mbcnt_lo_u32_b32 v200, -1, 0
	v_mbcnt_hi_u32_b32 v200, -1, v200
	v_lshlrev_b32_e32 v201, 3, v200
	v_lshlrev_b32_e32 v200, 4, v200
	s_load_dwordx2 s[16:17], s[54:55], 0xd8
	s_add_i32 s18, s3, 0x4000
	s_lshl_b32 s19, s18, 12
	s_waitcnt lgkmcnt(0)
	s_add_u32 s16, s16, s19
	s_addc_u32 s17, s17, 0
	global_load_dwordx4 v[6:9], v200, s[16:17] offset:0
	global_load_dwordx4 v[10:13], v200, s[16:17] offset:1024
	global_load_dwordx4 v[14:17], v200, s[16:17] offset:2048
	global_load_dwordx4 v[18:21], v200, s[16:17] offset:3072
	s_lshl_b32 s19, s3, 12
	s_add_u32 s20, s8, s19
	s_addc_u32 s21, s9, 0
	s_add_u32 s20, s20, 0x15e00000
	s_addc_u32 s21, s21, 0
	s_mul_i32 s31, s2, 0x3000
	v_mov_b32_e32 v205, 0
	s_cmp_eq_u32 s5, 7
	s_cbranch_scc1 .Lsn_final_p
	s_cmp_eq_u32 s6, 0
	s_cbranch_scc1 .Lsn_ffn_p
	s_add_i32 s24, s25, 1
	s_movk_i32 s26, 0x48
	s_mul_i32 s27, s24, 0x6000
	s_branch .Lsn_p_done

.Lsn_p_done:
	s_load_dwordx2 s[28:29], s[54:55], s26
	s_lshl_b32 s24, s24, 12
	s_waitcnt lgkmcnt(0)
	s_add_u32 s28, s28, s24
	s_addc_u32 s29, s29, 0
	s_add_i32 m0, s31, 0x0
	v_add_u32_e32 v204, 0x0, v200
	v_lshl_add_u64 v[206:207], s[28:29], 0, v[204:205]
	global_load_lds_dwordx4 v[206:207], off
	s_add_i32 m0, s31, 0x400
	v_add_u32_e32 v204, 0x400, v200
	v_lshl_add_u64 v[206:207], s[28:29], 0, v[204:205]
	global_load_lds_dwordx4 v[206:207], off
	s_add_i32 m0, s31, 0x800
	v_add_u32_e32 v204, 0x800, v200
	v_lshl_add_u64 v[206:207], s[28:29], 0, v[204:205]
	global_load_lds_dwordx4 v[206:207], off
	s_add_i32 m0, s31, 0xc00
	v_add_u32_e32 v204, 0xc00, v200
	v_lshl_add_u64 v[206:207], s[28:29], 0, v[204:205]
	global_load_lds_dwordx4 v[206:207], off
	s_cmp_eq_u32 s5, 7
	s_cbranch_scc1 .Lsn_nomod_e
	v_readlane_b32 s28, v253, 34
	v_readlane_b32 s29, v253, 35
	s_lshr_b32 s30, s3, 3
	s_add_i32 s30, s30, 2
	s_mul_i32 s30, s30, 0x18000
	s_add_i32 s30, s30, s27
	s_add_u32 s28, s28, s30
	s_addc_u32 s29, s29, 0
	s_add_i32 m0, s31, 0x1000
	v_add_u32_e32 v204, 0x0, v200
	v_lshl_add_u64 v[206:207], s[28:29], 0, v[204:205]
	global_load_lds_dwordx4 v[206:207], off
	s_add_i32 m0, s31, 0x1400
	v_add_u32_e32 v204, 0x400, v200
	v_lshl_add_u64 v[206:207], s[28:29], 0, v[204:205]
	global_load_lds_dwordx4 v[206:207], off
	s_add_i32 m0, s31, 0x1800
	v_add_u32_e32 v204, 0x800, v200
	v_lshl_add_u64 v[206:207], s[28:29], 0, v[204:205]
	global_load_lds_dwordx4 v[206:207], off
	s_add_i32 m0, s31, 0x1c00
	v_add_u32_e32 v204, 0xc00, v200
	v_lshl_add_u64 v[206:207], s[28:29], 0, v[204:205]
	global_load_lds_dwordx4 v[206:207], off
	s_add_u32 s28, s28, 0x1000
	s_addc_u32 s29, s29, 0
	s_add_i32 m0, s31, 0x2000
	v_add_u32_e32 v204, 0x0, v200
	v_lshl_add_u64 v[206:207], s[28:29], 0, v[204:205]
	global_load_lds_dwordx4 v[206:207], off
	s_add_i32 m0, s31, 0x2400
	v_add_u32_e32 v204, 0x400, v200
	v_lshl_add_u64 v[206:207], s[28:29], 0, v[204:205]
	global_load_lds_dwordx4 v[206:207], off
	s_add_i32 m0, s31, 0x2800
	v_add_u32_e32 v204, 0x800, v200
	v_lshl_add_u64 v[206:207], s[28:29], 0, v[204:205]
	global_load_lds_dwordx4 v[206:207], off
	s_add_i32 m0, s31, 0x2c00
	v_add_u32_e32 v204, 0xc00, v200
	v_lshl_add_u64 v[206:207], s[28:29], 0, v[204:205]
	global_load_lds_dwordx4 v[206:207], off
.Lsn_nomod_e:
	s_add_u32 s22, s20, 0x0
	s_addc_u32 s23, s21, 0
	global_load_dwordx4 v[22:25], v200, s[22:23] offset:0 sc1
	global_load_dwordx4 v[26:29], v200, s[22:23] offset:1024 sc1
	global_load_dwordx4 v[30:33], v200, s[22:23] offset:2048 sc1
	global_load_dwordx4 v[34:37], v200, s[22:23] offset:3072 sc1
	s_add_u32 s22, s20, 0x400000
	s_addc_u32 s23, s21, 0
	global_load_dwordx4 v[38:41], v200, s[22:23] offset:0 sc1
	global_load_dwordx4 v[42:45], v200, s[22:23] offset:1024 sc1
	global_load_dwordx4 v[46:49], v200, s[22:23] offset:2048 sc1
	global_load_dwordx4 v[50:53], v200, s[22:23] offset:3072 sc1
	s_add_u32 s22, s20, 0x800000
	s_addc_u32 s23, s21, 0
	global_load_dwordx4 v[54:57], v200, s[22:23] offset:0 sc1
	global_load_dwordx4 v[58:61], v200, s[22:23] offset:1024 sc1
	global_load_dwordx4 v[62:65], v200, s[22:23] offset:2048 sc1
	global_load_dwordx4 v[66:69], v200, s[22:23] offset:3072 sc1
	s_add_u32 s22, s20, 0xc00000
	s_addc_u32 s23, s21, 0
	global_load_dwordx4 v[70:73], v200, s[22:23] offset:0 sc1
	global_load_dwordx4 v[74:77], v200, s[22:23] offset:1024 sc1
	global_load_dwordx4 v[78:81], v200, s[22:23] offset:2048 sc1
	global_load_dwordx4 v[82:85], v200, s[22:23] offset:3072 sc1
	s_add_u32 s22, s20, 0x1000000
	s_addc_u32 s23, s21, 0
	global_load_dwordx4 v[86:89], v200, s[22:23] offset:0 sc1
	global_load_dwordx4 v[90:93], v200, s[22:23] offset:1024 sc1
	global_load_dwordx4 v[94:97], v200, s[22:23] offset:2048 sc1
	global_load_dwordx4 v[98:101], v200, s[22:23] offset:3072 sc1
	s_add_u32 s22, s20, 0x1400000
	s_addc_u32 s23, s21, 0
	global_load_dwordx4 v[102:105], v200, s[22:23] offset:0 sc1
	global_load_dwordx4 v[106:109], v200, s[22:23] offset:1024 sc1
	global_load_dwordx4 v[110:113], v200, s[22:23] offset:2048 sc1
	global_load_dwordx4 v[114:117], v200, s[22:23] offset:3072 sc1
	s_add_u32 s22, s20, 0x1800000
	s_addc_u32 s23, s21, 0
	global_load_dwordx4 v[118:121], v200, s[22:23] offset:0 sc1
	global_load_dwordx4 v[122:125], v200, s[22:23] offset:1024 sc1
	global_load_dwordx4 v[126:129], v200, s[22:23] offset:2048 sc1
	global_load_dwordx4 v[130:133], v200, s[22:23] offset:3072 sc1
	s_add_u32 s22, s20, 0x1c00000
	s_addc_u32 s23, s21, 0
	global_load_dwordx4 v[134:137], v200, s[22:23] offset:0 sc1
	global_load_dwordx4 v[138:141], v200, s[22:23] offset:1024 sc1
	global_load_dwordx4 v[142:145], v200, s[22:23] offset:2048 sc1
	global_load_dwordx4 v[146:149], v200, s[22:23] offset:3072 sc1
	s_cmp_lg_u32 s7, 44
	s_cbranch_scc1 .Lsn_l8
	s_add_u32 s22, s20, 0x2000000
	s_addc_u32 s23, s21, 0
	global_load_dwordx4 v[150:153], v200, s[22:23] offset:0 sc1
	global_load_dwordx4 v[154:157], v200, s[22:23] offset:1024 sc1
	global_load_dwordx4 v[158:161], v200, s[22:23] offset:2048 sc1
	global_load_dwordx4 v[162:165], v200, s[22:23] offset:3072 sc1
	s_add_u32 s22, s20, 0x2400000
	s_addc_u32 s23, s21, 0
	global_load_dwordx4 v[166:169], v200, s[22:23] offset:0 sc1
	global_load_dwordx4 v[170:173], v200, s[22:23] offset:1024 sc1
	global_load_dwordx4 v[174:177], v200, s[22:23] offset:2048 sc1
	global_load_dwordx4 v[178:181], v200, s[22:23] offset:3072 sc1
	s_add_u32 s22, s20, 0x2800000
	s_addc_u32 s23, s21, 0
	global_load_dwordx4 v[182:185], v200, s[22:23] offset:0 sc1
	global_load_dwordx4 v[186:189], v200, s[22:23] offset:1024 sc1
	global_load_dwordx4 v[190:193], v200, s[22:23] offset:2048 sc1
	global_load_dwordx4 v[194:197], v200, s[22:23] offset:3072 sc1

.Lsn_sum:
	v_add_u32_e32 v204, s31, v200
	ds_read_b128 v[22:25], v204 offset:0
	ds_read_b128 v[26:29], v204 offset:1024
	ds_read_b128 v[30:33], v204 offset:2048
	ds_read_b128 v[34:37], v204 offset:3072
	v_mov_b32_e32 v38, 0
	v_mov_b32_e32 v54, 0
	v_mov_b32_e32 v39, 0
	v_mov_b32_e32 v55, 0
	v_mov_b32_e32 v40, 0
	v_mov_b32_e32 v56, 0
	v_mov_b32_e32 v41, 0
	v_mov_b32_e32 v57, 0
	v_mov_b32_e32 v42, 0
	v_mov_b32_e32 v58, 0
	v_mov_b32_e32 v43, 0
	v_mov_b32_e32 v59, 0
	v_mov_b32_e32 v44, 0
	v_mov_b32_e32 v60, 0
	v_mov_b32_e32 v45, 0
	v_mov_b32_e32 v61, 0
	v_mov_b32_e32 v46, 0
	v_mov_b32_e32 v62, 0
	v_mov_b32_e32 v47, 0
	v_mov_b32_e32 v63, 0
	v_mov_b32_e32 v48, 0
	v_mov_b32_e32 v64, 0
	v_mov_b32_e32 v49, 0
	v_mov_b32_e32 v65, 0
	v_mov_b32_e32 v50, 0
	v_mov_b32_e32 v66, 0
	v_mov_b32_e32 v51, 0
	v_mov_b32_e32 v67, 0
	v_mov_b32_e32 v52, 0
	v_mov_b32_e32 v68, 0
	v_mov_b32_e32 v53, 0
	v_mov_b32_e32 v69, 0
	s_cmp_eq_u32 s5, 7
	s_cbranch_scc1 .Lsn_nomod
	ds_read_b128 v[38:41], v204 offset:4096
	ds_read_b128 v[42:45], v204 offset:5120
	ds_read_b128 v[46:49], v204 offset:6144
	ds_read_b128 v[50:53], v204 offset:7168
	ds_read_b128 v[54:57], v204 offset:8192
	ds_read_b128 v[58:61], v204 offset:9216
	ds_read_b128 v[62:65], v204 offset:10240
	ds_read_b128 v[66:69], v204 offset:11264
.Lsn_nomod:
	v_pk_mul_f32 v[202:203], v[6:7], v[6:7]
	v_pk_fma_f32 v[202:203], v[8:9], v[8:9], v[202:203]
	v_pk_fma_f32 v[202:203], v[10:11], v[10:11], v[202:203]
	v_pk_fma_f32 v[202:203], v[12:13], v[12:13], v[202:203]
	v_pk_fma_f32 v[202:203], v[14:15], v[14:15], v[202:203]
	v_pk_fma_f32 v[202:203], v[16:17], v[16:17], v[202:203]
	v_pk_fma_f32 v[202:203], v[18:19], v[18:19], v[202:203]
	v_pk_fma_f32 v[202:203], v[20:21], v[20:21], v[202:203]
	v_add_f32_e32 v202, v202, v203
	s_nop 1
	v_add_f32_dpp v202, v202, v202 quad_perm:[1,0,3,2] row_mask:0xf bank_mask:0xf
	s_nop 1
	v_add_f32_dpp v202, v202, v202 quad_perm:[2,3,0,1] row_mask:0xf bank_mask:0xf
	s_nop 1
	v_add_f32_dpp v202, v202, v202 row_half_mirror row_mask:0xf bank_mask:0xf
	s_nop 1
	v_add_f32_dpp v202, v202, v202 row_mirror row_mask:0xf bank_mask:0xf
	s_nop 1
	v_add_f32_dpp v202, v202, v202 row_bcast:15 row_mask:0xa bank_mask:0xf
	s_nop 1
	v_add_f32_dpp v202, v202, v202 row_bcast:31 row_mask:0xc bank_mask:0xf
	s_nop 1
	v_readlane_b32 s30, v202, 63
	s_nop 1
	v_mov_b32_e32 v204, s30
	v_fmamk_f32 v204, v204, 0x3a800000, v232
	v_rsq_f32_e32 v204, v204
	s_nop 0
	v_mov_b32_e32 v205, v204
	s_waitcnt vmcnt(0)
	s_waitcnt lgkmcnt(0)
	s_lshl_b32 s19, s18, 11
	s_add_u32 s30, s8, s19
	s_addc_u32 s31, s9, 0
	s_add_u32 s30, s30, 0x7400000
	s_addc_u32 s31, s31, 0
	s_cmp_eq_u32 s5, 7
	s_cbranch_scc1 .Lsn_final_out
	global_store_dwordx4 v200, v[6:9], s[16:17] offset:0
	global_store_dwordx4 v200, v[10:13], s[16:17] offset:1024
	global_store_dwordx4 v200, v[14:17], s[16:17] offset:2048
	global_store_dwordx4 v200, v[18:21], s[16:17] offset:3072
	v_pk_add_f32 v[54:55], v[54:55], 1.0 op_sel_hi:[1,0]
	v_pk_mul_f32 v[22:23], v[22:23], v[54:55]
	v_pk_mul_f32 v[206:207], v[6:7], v[204:205]
	v_pk_fma_f32 v[206:207], v[206:207], v[22:23], v[38:39]
	v_pk_add_f32 v[56:57], v[56:57], 1.0 op_sel_hi:[1,0]
	v_pk_mul_f32 v[24:25], v[24:25], v[56:57]
	v_pk_mul_f32 v[208:209], v[8:9], v[204:205]
	v_pk_fma_f32 v[208:209], v[208:209], v[24:25], v[40:41]
	v_cvt_pk_bf16_f32 v210, v206, v207
	v_cvt_pk_bf16_f32 v211, v208, v209
	global_store_dwordx2 v201, v[210:211], s[30:31] offset:0
	v_pk_add_f32 v[58:59], v[58:59], 1.0 op_sel_hi:[1,0]
	v_pk_mul_f32 v[26:27], v[26:27], v[58:59]
	v_pk_mul_f32 v[206:207], v[10:11], v[204:205]
	v_pk_fma_f32 v[206:207], v[206:207], v[26:27], v[42:43]
	v_pk_add_f32 v[60:61], v[60:61], 1.0 op_sel_hi:[1,0]
	v_pk_mul_f32 v[28:29], v[28:29], v[60:61]
	v_pk_mul_f32 v[208:209], v[12:13], v[204:205]
	v_pk_fma_f32 v[208:209], v[208:209], v[28:29], v[44:45]
	v_cvt_pk_bf16_f32 v212, v206, v207
	v_cvt_pk_bf16_f32 v213, v208, v209
	global_store_dwordx2 v201, v[212:213], s[30:31] offset:512
	v_pk_add_f32 v[62:63], v[62:63], 1.0 op_sel_hi:[1,0]
	v_pk_mul_f32 v[30:31], v[30:31], v[62:63]
	v_pk_mul_f32 v[206:207], v[14:15], v[204:205]
	v_pk_fma_f32 v[206:207], v[206:207], v[30:31], v[46:47]
	v_pk_add_f32 v[64:65], v[64:65], 1.0 op_sel_hi:[1,0]
	v_pk_mul_f32 v[32:33], v[32:33], v[64:65]
	v_pk_mul_f32 v[208:209], v[16:17], v[204:205]
	v_pk_fma_f32 v[208:209], v[208:209], v[32:33], v[48:49]
	v_cvt_pk_bf16_f32 v214, v206, v207
	v_cvt_pk_bf16_f32 v215, v208, v209
	global_store_dwordx2 v201, v[214:215], s[30:31] offset:1024
	v_pk_add_f32 v[66:67], v[66:67], 1.0 op_sel_hi:[1,0]
	v_pk_mul_f32 v[34:35], v[34:35], v[66:67]
	v_pk_mul_f32 v[206:207], v[18:19], v[204:205]
	v_pk_fma_f32 v[206:207], v[206:207], v[34:35], v[50:51]
	v_pk_add_f32 v[68:69], v[68:69], 1.0 op_sel_hi:[1,0]
	v_pk_mul_f32 v[36:37], v[36:37], v[68:69]
	v_pk_mul_f32 v[208:209], v[20:21], v[204:205]
	v_pk_fma_f32 v[208:209], v[208:209], v[36:37], v[52:53]
	v_cvt_pk_bf16_f32 v216, v206, v207
	v_cvt_pk_bf16_f32 v217, v208, v209
	global_store_dwordx2 v201, v[216:217], s[30:31] offset:1536
	s_branch .Lsn_done
